# prep: step-2 beta/alpha/dt_bias/a_log loads and block-1 q/k/v conv loads prefetched at item start
# speedup vs baseline: 1.0005x; 1.0005x over previous
.LBB0_1116:
	s_and_b32 s54, s2, 3
	s_lshl_b32 s55, s2, 4
	s_andn2_b32 s55, s55, 63
	s_lshl_b32 s3, s54, 7
	v_or_b32_e32 v180, s55, v102
	v_ashrrev_i32_e32 v181, 31, v180
	v_lshlrev_b64 v[180:181], 6, v[180:181]
	v_lshl_add_u64 v[180:181], v[84:85], 0, v[180:181]
	s_lshl_b32 s98, s54, 2
	s_mov_b32 s99, 0
	v_lshl_add_u64 v[180:181], v[180:181], 0, s[98:99]
	global_load_dword v193, v[180:181], off
	global_load_dword v204, v[180:181], off offset:32
	v_or_b32_e32 v180, s54, v104
	v_ashrrev_i32_e32 v181, 31, v180
	v_lshlrev_b64 v[180:181], 2, v[180:181]
	v_readlane_b32 s98, v250, 12
	v_readlane_b32 s99, v250, 13
	s_nop 3
	v_lshl_add_u64 v[222:223], s[98:99], 0, v[180:181]
	global_load_dword v205, v[222:223], off
	v_readlane_b32 s98, v250, 10
	v_readlane_b32 s99, v250, 11
	s_nop 3
	v_lshl_add_u64 v[222:223], s[98:99], 0, v[180:181]
	global_load_dword v221, v[222:223], off
	v_add_u32_e32 v12, s55, v103
	v_mov_b64_e32 v[0:1], s[46:47]
	s_movk_i32 s0, 0xc00
	v_or_b32_e32 v192, s3, v64
	v_mad_i64_i32 v[0:1], s[0:1], v12, s0, v[0:1]
	v_lshlrev_b32_e32 v176, 1, v192
	v_lshl_add_u64 v[94:95], v[0:1], 0, v[176:177]
	flat_load_dwordx4 v[0:3], v[94:95]
	flat_load_dwordx4 v[36:39], v[94:95] offset:16
	global_load_dwordx4 v[224:227], v[94:95], off offset:1024
	global_load_dwordx4 v[228:231], v[94:95], off offset:1040
	s_mov_b32 s0, 0x8000
	v_cmp_gt_i32_e32 vcc, s0, v12
	v_mov_b32_e32 v40, 0
	v_mov_b32_e32 v44, 0
	v_cndmask_b32_e32 v8, v211, v212, vcc
	v_and_b32_e32 v9, v8, v12
	v_cmp_ne_u32_e64 s[92:93], 0, v9
	v_mov_b32_e32 v45, 0
	v_mov_b32_e32 v46, 0
	v_mov_b32_e32 v47, 0
	v_mov_b32_e32 v4, 0
	v_mov_b32_e32 v5, 0
	v_mov_b32_e32 v6, 0
	v_mov_b32_e32 v7, 0
	s_and_saveexec_b64 s[0:1], s[92:93]
	s_cbranch_execz .LBB0_1118
	v_add_co_u32_e32 v4, vcc, 0xfffff400, v94
	s_nop 1
	v_addc_co_u32_e32 v5, vcc, -1, v95, vcc
	v_add_co_u32_e32 v10, vcc, 0xfffff410, v94
	s_nop 1
	v_addc_co_u32_e32 v11, vcc, -1, v95, vcc
	flat_load_dwordx4 v[4:7], v[4:5]
	s_nop 0
	flat_load_dwordx4 v[44:47], v[10:11]
	v_add_co_u32_e32 v180, vcc, 0xfffff800, v94
	s_nop 1
	v_addc_co_u32_e32 v181, vcc, -1, v95, vcc
	global_load_dwordx4 v[232:235], v[180:181], off
	global_load_dwordx4 v[236:239], v[180:181], off offset:16
.LBB0_1118:
	s_or_b64 exec, exec, s[0:1]
	v_cmp_ne_u32_e64 s[94:95], v9, v8
	v_mov_b32_e32 v41, 0
	v_mov_b32_e32 v42, 0
	v_mov_b32_e32 v43, 0
	v_mov_b32_e32 v8, 0
	v_mov_b32_e32 v9, 0
	v_mov_b32_e32 v10, 0
	v_mov_b32_e32 v11, 0
	s_and_saveexec_b64 s[0:1], s[94:95]
	s_cbranch_execz .LBB0_1120
	flat_load_dwordx4 v[8:11], v[94:95] offset:3072
	flat_load_dwordx4 v[40:43], v[94:95] offset:3088
	v_add_co_u32_e32 v222, vcc, 0x1000, v94
	s_nop 1
	v_addc_co_u32_e32 v223, vcc, 0, v95, vcc
	global_load_dwordx4 v[240:243], v[222:223], off
	global_load_dwordx4 v[244:247], v[222:223], off offset:16
.LBB0_1120:
	s_or_b64 exec, exec, s[0:1]
	v_lshlrev_b32_e32 v176, 2, v192
	v_lshl_add_u64 v[92:93], s[82:83], 0, v[176:177]
	s_mov_b64 s[0:1], 0x1800
	v_ashrrev_i32_e32 v13, 31, v12
	v_lshl_add_u64 v[20:21], v[92:93], 0, s[0:1]
	s_mov_b64 s[0:1], 0x3000
	v_lshlrev_b64 v[60:61], 10, v[12:13]
	v_lshl_add_u64 v[32:33], v[92:93], 0, s[0:1]
	s_movk_i32 s0, 0x1000
	v_lshl_add_u64 v[12:13], s[84:85], 0, v[60:61]
	s_lshl_b32 s30, s3, 1
	v_add_co_u32_e32 v16, vcc, s0, v92
	v_lshl_add_u64 v[12:13], v[12:13], 0, s[30:31]
	v_mov_b32_e32 v87, v177
	v_addc_co_u32_e32 v17, vcc, 0, v93, vcc
	v_lshl_add_u64 v[62:63], v[12:13], 0, v[86:87]
	global_load_dwordx4 v[194:197], v176, s[82:83] offset:48
	global_load_dwordx4 v[48:51], v176, s[82:83] offset:32
	global_load_dwordx4 v[24:27], v176, s[82:83] offset:16
	global_load_dwordx4 v[12:15], v176, s[82:83]
	s_nop 0
	global_load_dwordx4 v[16:19], v[16:17], off offset:2048
	s_nop 0
	global_load_dwordx4 v[198:201], v[20:21], off offset:48
	global_load_dwordx4 v[52:55], v[20:21], off offset:32
	global_load_dwordx4 v[28:31], v[20:21], off offset:16
	s_movk_i32 s0, 0x3000
	s_waitcnt vmcnt(0) lgkmcnt(0)
	v_lshlrev_b32_e32 v20, 16, v39
	v_and_b32_e32 v21, 0xffff0000, v39
	v_add_co_u32_e32 v98, vcc, s0, v92
	v_lshlrev_b32_e32 v22, 16, v47
	v_and_b32_e32 v23, 0xffff0000, v47
	v_addc_co_u32_e32 v99, vcc, 0, v93, vcc
	v_lshlrev_b32_e32 v100, 16, v43
	v_and_b32_e32 v101, 0xffff0000, v43
	v_and_b32_e32 v47, 0xffff0000, v38
	s_mov_b32 s0, 0x800000
	v_pk_mul_f32 v[20:21], v[200:201], v[20:21]
	s_nop 0
	v_pk_fma_f32 v[96:97], v[196:197], v[22:23], v[20:21]
	global_load_dwordx4 v[20:23], v[98:99], off
	global_load_dwordx4 v[200:203], v[32:33], off offset:48
	global_load_dwordx4 v[56:59], v[32:33], off offset:32
	s_nop 0
	global_load_dwordx4 v[32:35], v[32:33], off offset:16
	v_lshlrev_b32_e32 v196, 16, v46
	v_and_b32_e32 v197, 0xffff0000, v46
	v_lshlrev_b32_e32 v46, 16, v38
	v_lshlrev_b32_e32 v38, 16, v42
	s_waitcnt vmcnt(2)
	v_pk_fma_f32 v[96:97], v[202:203], v[100:101], v[96:97]
	s_nop 0
	v_mul_f32_e32 v39, 0xbfb8aa3b, v96
	v_exp_f32_e32 v39, v39
	s_nop 0
	v_add_f32_e32 v39, 1.0, v39
	v_rcp_f32_e32 v100, v39
	v_mul_f32_e32 v39, 0xbfb8aa3b, v97
	v_exp_f32_e32 v39, v39
	s_nop 0
	v_add_f32_e32 v39, 1.0, v39
	v_rcp_f32_e32 v101, v39
	v_and_b32_e32 v39, 0xffff0000, v42
	v_pk_mul_f32 v[42:43], v[198:199], v[46:47]
	v_lshlrev_b32_e32 v46, 16, v45
	v_pk_fma_f32 v[42:43], v[194:195], v[196:197], v[42:43]
	v_lshlrev_b32_e32 v194, 16, v37
	v_and_b32_e32 v195, 0xffff0000, v37
	v_and_b32_e32 v47, 0xffff0000, v45
	v_pk_mul_f32 v[54:55], v[54:55], v[194:195]
	v_lshlrev_b32_e32 v196, 16, v41
	v_and_b32_e32 v197, 0xffff0000, v41
	v_pk_fma_f32 v[46:47], v[50:51], v[46:47], v[54:55]
	v_lshlrev_b32_e32 v54, 16, v44
	s_waitcnt vmcnt(1)
	v_pk_fma_f32 v[46:47], v[58:59], v[196:197], v[46:47]
	v_and_b32_e32 v55, 0xffff0000, v44
	v_mul_f32_e32 v37, 0xbfb8aa3b, v46
	v_exp_f32_e32 v37, v37
	v_lshlrev_b32_e32 v44, 16, v36
	v_and_b32_e32 v45, 0xffff0000, v36
	v_lshlrev_b32_e32 v36, 16, v40
	v_add_f32_e32 v37, 1.0, v37
	v_rcp_f32_e32 v50, v37
	v_mul_f32_e32 v37, 0xbfb8aa3b, v47
	v_exp_f32_e32 v37, v37
	v_pk_fma_f32 v[38:39], v[200:201], v[38:39], v[42:43]
	v_pk_mul_f32 v[96:97], v[96:97], v[100:101]
	v_mul_f32_e32 v42, 0xbfb8aa3b, v38
	v_add_f32_e32 v37, 1.0, v37
	v_rcp_f32_e32 v51, v37
	v_and_b32_e32 v37, 0xffff0000, v40
	v_pk_mul_f32 v[40:41], v[52:53], v[44:45]
	v_lshlrev_b32_e32 v44, 16, v7
	v_pk_fma_f32 v[40:41], v[48:49], v[54:55], v[40:41]
	v_lshlrev_b32_e32 v48, 16, v3
	v_and_b32_e32 v49, 0xffff0000, v3
	v_and_b32_e32 v45, 0xffff0000, v7
	v_pk_mul_f32 v[30:31], v[30:31], v[48:49]
	v_lshlrev_b32_e32 v52, 16, v11
	v_and_b32_e32 v53, 0xffff0000, v11
	v_pk_fma_f32 v[26:27], v[26:27], v[44:45], v[30:31]
	v_and_b32_e32 v7, 0xffff0000, v2
	s_waitcnt vmcnt(0)
	v_pk_fma_f32 v[26:27], v[34:35], v[52:53], v[26:27]
	v_lshlrev_b32_e32 v34, 16, v6
	v_mul_f32_e32 v3, 0xbfb8aa3b, v26
	v_exp_f32_e32 v3, v3
	v_and_b32_e32 v35, 0xffff0000, v6
	v_lshlrev_b32_e32 v6, 16, v2
	v_pk_mul_f32 v[6:7], v[28:29], v[6:7]
	v_add_f32_e32 v3, 1.0, v3
	v_rcp_f32_e32 v30, v3
	v_mul_f32_e32 v3, 0xbfb8aa3b, v27
	v_exp_f32_e32 v3, v3
	v_pk_fma_f32 v[6:7], v[24:25], v[34:35], v[6:7]
	v_lshlrev_b32_e32 v24, 16, v1
	v_and_b32_e32 v25, 0xffff0000, v1
	v_add_f32_e32 v3, 1.0, v3
	v_rcp_f32_e32 v31, v3
	v_lshlrev_b32_e32 v2, 16, v10
	v_and_b32_e32 v3, 0xffff0000, v10
	v_lshlrev_b32_e32 v10, 16, v5
	v_and_b32_e32 v11, 0xffff0000, v5
	v_pk_mul_f32 v[18:19], v[18:19], v[24:25]
	v_lshlrev_b32_e32 v28, 16, v9
	v_and_b32_e32 v29, 0xffff0000, v9
	v_pk_fma_f32 v[10:11], v[14:15], v[10:11], v[18:19]
	v_lshlrev_b32_e32 v18, 16, v4
	v_pk_fma_f32 v[10:11], v[22:23], v[28:29], v[10:11]
	v_and_b32_e32 v19, 0xffff0000, v4
	v_mul_f32_e32 v1, 0xbfb8aa3b, v10
	v_exp_f32_e32 v1, v1
	v_lshlrev_b32_e32 v4, 16, v0
	v_and_b32_e32 v5, 0xffff0000, v0
	v_pk_mul_f32 v[4:5], v[16:17], v[4:5]
	v_add_f32_e32 v1, 1.0, v1
	v_rcp_f32_e32 v14, v1
	v_mul_f32_e32 v1, 0xbfb8aa3b, v11
	v_exp_f32_e32 v1, v1
	v_lshlrev_b32_e32 v0, 16, v8
	v_pk_fma_f32 v[4:5], v[12:13], v[18:19], v[4:5]
	v_pk_fma_f32 v[2:3], v[32:33], v[2:3], v[6:7]
	v_add_f32_e32 v1, 1.0, v1
	v_rcp_f32_e32 v15, v1
	v_and_b32_e32 v1, 0xffff0000, v8
	v_pk_fma_f32 v[0:1], v[20:21], v[0:1], v[4:5]
	v_mul_f32_e32 v6, 0xbfb8aa3b, v2
	v_mul_f32_e32 v4, 0xbfb8aa3b, v0
	v_mul_f32_e32 v5, 0xbfb8aa3b, v1
	v_exp_f32_e32 v4, v4
	v_exp_f32_e32 v5, v5
	v_mul_f32_e32 v7, 0xbfb8aa3b, v3
	v_exp_f32_e32 v6, v6
	v_exp_f32_e32 v7, v7
	v_add_f32_e32 v4, 1.0, v4
	v_add_f32_e32 v5, 1.0, v5
	v_pk_fma_f32 v[36:37], v[56:57], v[36:37], v[40:41]
	v_rcp_f32_e32 v4, v4
	v_rcp_f32_e32 v5, v5
	v_mul_f32_e32 v40, 0xbfb8aa3b, v36
	v_mul_f32_e32 v41, 0xbfb8aa3b, v37
	v_exp_f32_e32 v40, v40
	v_exp_f32_e32 v41, v41
	v_add_f32_e32 v6, 1.0, v6
	v_add_f32_e32 v7, 1.0, v7
	v_rcp_f32_e32 v6, v6
	v_rcp_f32_e32 v7, v7
	v_pk_mul_f32 v[0:1], v[0:1], v[4:5]
	v_mul_f32_e32 v43, 0xbfb8aa3b, v39
	v_pk_mul_f32 v[10:11], v[10:11], v[14:15]
	v_pk_mul_f32 v[4:5], v[0:1], v[0:1]
	v_exp_f32_e32 v42, v42
	v_exp_f32_e32 v43, v43
	v_add_f32_e32 v40, 1.0, v40
	v_add_f32_e32 v41, 1.0, v41
	v_pk_mul_f32 v[14:15], v[10:11], v[10:11]
	v_add_f32_e32 v4, v4, v5
	v_rcp_f32_e32 v40, v40
	v_rcp_f32_e32 v41, v41
	v_pk_mul_f32 v[2:3], v[2:3], v[6:7]
	v_add_f32_e32 v4, v4, v14
	v_pk_mul_f32 v[6:7], v[2:3], v[2:3]
	v_add_f32_e32 v4, v4, v15
	v_pk_mul_f32 v[26:27], v[26:27], v[30:31]
	v_add_f32_e32 v4, v4, v6
	v_add_f32_e32 v42, 1.0, v42
	v_add_f32_e32 v43, 1.0, v43
	v_pk_mul_f32 v[30:31], v[26:27], v[26:27]
	v_add_f32_e32 v4, v4, v7
	v_rcp_f32_e32 v42, v42
	v_rcp_f32_e32 v43, v43
	v_pk_mul_f32 v[36:37], v[36:37], v[40:41]
	v_add_f32_e32 v4, v4, v30
	v_pk_mul_f32 v[40:41], v[36:37], v[36:37]
	v_add_f32_e32 v4, v4, v31
	v_pk_mul_f32 v[46:47], v[46:47], v[50:51]
	v_add_f32_e32 v4, v4, v40
	v_pk_mul_f32 v[50:51], v[46:47], v[46:47]
	v_add_f32_e32 v4, v4, v41
	v_pk_mul_f32 v[38:39], v[38:39], v[42:43]
	v_add_f32_e32 v4, v4, v50
	v_pk_mul_f32 v[42:43], v[38:39], v[38:39]
	v_add_f32_e32 v4, v4, v51
	v_add_f32_e32 v4, v4, v42
	v_pk_mul_f32 v[100:101], v[96:97], v[96:97]
	v_add_f32_e32 v4, v4, v43
	v_add_f32_e32 v4, v4, v100
	v_add_f32_e32 v4, v4, v101
	ds_bpermute_b32 v5, v108, v4
	v_mov_b32_e32 v40, 0
	v_mov_b32_e32 v44, 0
	v_mov_b32_e32 v45, 0
	s_waitcnt lgkmcnt(0)
	v_add_f32_e32 v4, v4, v5
	ds_bpermute_b32 v5, v109, v4
	s_waitcnt lgkmcnt(0)
	v_add_f32_e32 v4, v4, v5
	ds_bpermute_b32 v5, v110, v4
	s_waitcnt lgkmcnt(0)
	v_add_f32_e32 v4, v4, v5
	v_add_f32_e32 v4, 0x358637bd, v4
	v_cmp_gt_f32_e32 vcc, s0, v4
	v_mul_f32_e32 v5, 0x4b800000, v4
	s_mov_b64 s[0:1], 0x400
	v_cndmask_b32_e32 v4, v4, v5, vcc
	v_rsq_f32_e32 v4, v4
	s_nop 0
	v_mul_f32_e32 v5, 0x45800000, v4
	v_cndmask_b32_e32 v4, v4, v5, vcc
	v_mul_f32_e32 v4, 0x3db504f3, v4
	v_pk_mul_f32 v[6:7], v[0:1], v[4:5] op_sel_hi:[1,0]
	v_pk_mul_f32 v[8:9], v[10:11], v[4:5] op_sel_hi:[1,0]
	v_pk_mul_f32 v[10:11], v[2:3], v[4:5] op_sel_hi:[1,0]
	v_pk_mul_f32 v[12:13], v[26:27], v[4:5] op_sel_hi:[1,0]
	v_pk_mul_f32 v[0:1], v[36:37], v[4:5] op_sel_hi:[1,0]
	v_pk_mul_f32 v[2:3], v[46:47], v[4:5] op_sel_hi:[1,0]
	v_pk_mul_f32 v[14:15], v[38:39], v[4:5] op_sel_hi:[1,0]
	v_pk_mul_f32 v[4:5], v[96:97], v[4:5] op_sel_hi:[1,0]
	v_cvt_pk_bf16_f32 v0, v0, v1
	v_cvt_pk_bf16_f32 v1, v2, v3
	v_cvt_pk_bf16_f32 v3, v4, v5
	v_cvt_pk_bf16_f32 v4, v6, v7
	v_cvt_pk_bf16_f32 v5, v8, v9
	v_cvt_pk_bf16_f32 v6, v10, v11
	v_cvt_pk_bf16_f32 v7, v12, v13
	v_cvt_pk_bf16_f32 v2, v14, v15
	flat_store_dwordx4 v[62:63], v[4:7]
	flat_store_dwordx4 v[62:63], v[0:3] offset:16
	s_nop 1
	v_mov_b64_e32 v[0:1], v[224:225]
	v_mov_b64_e32 v[2:3], v[226:227]
	s_nop 0
	v_mov_b64_e32 v[36:37], v[228:229]
	v_mov_b64_e32 v[38:39], v[230:231]
	v_lshl_add_u64 v[12:13], v[94:95], 0, s[0:1]
	v_mov_b32_e32 v46, 0
	v_mov_b32_e32 v47, 0
	v_mov_b32_e32 v4, 0
	v_mov_b32_e32 v5, 0
	v_mov_b32_e32 v6, 0
	v_mov_b32_e32 v7, 0
	s_and_saveexec_b64 s[0:1], s[92:93]
	s_cbranch_execz .LBB0_1122
	v_add_co_u32_e32 v4, vcc, 0xfffff400, v12
	s_nop 1
	v_addc_co_u32_e32 v5, vcc, -1, v13, vcc
	v_add_co_u32_e32 v8, vcc, 0xfffff410, v12
	s_nop 1
	v_addc_co_u32_e32 v9, vcc, -1, v13, vcc
	v_mov_b64_e32 v[4:5], v[232:233]
	v_mov_b64_e32 v[6:7], v[234:235]
	s_nop 0
	v_mov_b64_e32 v[44:45], v[236:237]
	v_mov_b64_e32 v[46:47], v[238:239]
.LBB0_1122:
	s_or_b64 exec, exec, s[0:1]
	v_mov_b32_e32 v41, 0
	v_mov_b32_e32 v42, 0
	v_mov_b32_e32 v43, 0
	v_mov_b32_e32 v8, 0
	v_mov_b32_e32 v9, 0
	v_mov_b32_e32 v10, 0
	v_mov_b32_e32 v11, 0
	s_and_saveexec_b64 s[0:1], s[94:95]
	s_cbranch_execz .LBB0_1124
	v_mov_b64_e32 v[8:9], v[240:241]
	v_mov_b64_e32 v[10:11], v[242:243]
	v_mov_b64_e32 v[40:41], v[244:245]
	v_mov_b64_e32 v[42:43], v[246:247]

.LBB0_1128:
	s_or_b64 exec, exec, s[0:1]
	v_lshl_or_b32 v16, v192, 2, v213
	s_mov_b64 s[0:1], 0x2800
	global_load_dwordx4 v[56:59], v16, s[82:83]
	global_load_dwordx4 v[12:15], v16, s[82:83] offset:48
	global_load_dwordx4 v[20:23], v16, s[82:83] offset:32
	global_load_dwordx4 v[48:51], v16, s[82:83] offset:16
	v_lshl_add_u64 v[24:25], v[92:93], 0, s[0:1]
	global_load_dwordx4 v[94:97], v[96:97], off offset:2048
	s_nop 0
	global_load_dwordx4 v[16:19], v[24:25], off offset:48
	global_load_dwordx4 v[28:31], v[24:25], off offset:32
	global_load_dwordx4 v[52:55], v[24:25], off offset:16
	s_mov_b64 s[0:1], 0x4000
	s_waitcnt vmcnt(0) lgkmcnt(0)
	v_lshlrev_b32_e32 v32, 16, v40
	v_and_b32_e32 v33, 0xffff0000, v36
	v_lshl_add_u64 v[60:61], v[92:93], 0, s[0:1]
	v_lshlrev_b32_e32 v26, 16, v36
	v_and_b32_e32 v27, 0xffff0000, v40
	s_movk_i32 s0, 0x4000
	v_lshlrev_b32_e32 v98, 16, v44
	v_and_b32_e32 v99, 0xffff0000, v44
	v_lshlrev_b32_e32 v40, 16, v41
	v_and_b32_e32 v41, 0xffff0000, v41
	v_lshlrev_b32_e32 v44, 16, v45
	v_and_b32_e32 v45, 0xffff0000, v45
	v_readlane_b32 s56, v254, 55
	v_readlane_b32 s57, v254, 56
	v_mov_b32_e32 v25, v57
	v_mov_b32_e32 v57, v95
	v_mov_b32_e32 v24, v94
	v_pk_mul_f32 v[32:33], v[56:57], v[32:33]
	s_nop 0
	v_pk_fma_f32 v[56:57], v[24:25], v[26:27], v[32:33]
	v_add_co_u32_e32 v24, vcc, s0, v92
	s_nop 1
	v_addc_co_u32_e32 v25, vcc, 0, v93, vcc
	global_load_dwordx4 v[92:95], v[24:25], off
	s_nop 0
	global_load_dwordx4 v[24:27], v[60:61], off offset:48
	global_load_dwordx4 v[32:35], v[60:61], off offset:32
	s_nop 0
	global_load_dwordx4 v[60:63], v[60:61], off offset:16
	s_waitcnt vmcnt(3)
	v_pk_fma_f32 v[56:57], v[92:93], v[98:99], v[56:57]
	s_nop 0
	v_mul_f32_e32 v36, 0xbfb8aa3b, v56
	v_exp_f32_e32 v36, v36
	s_nop 0
	v_add_f32_e32 v36, 1.0, v36
	v_rcp_f32_e32 v92, v36
	v_mul_f32_e32 v36, 0xbfb8aa3b, v57
	v_exp_f32_e32 v36, v36
	s_nop 0
	v_add_f32_e32 v36, 1.0, v36
	v_rcp_f32_e32 v93, v36
	v_lshlrev_b32_e32 v36, 16, v37
	v_and_b32_e32 v37, 0xffff0000, v37
	v_pk_mul_f32 v[36:37], v[96:97], v[36:37]
	v_pk_mul_f32 v[56:57], v[56:57], v[92:93]
	v_pk_fma_f32 v[36:37], v[58:59], v[40:41], v[36:37]
	v_lshlrev_b32_e32 v58, 16, v46
	v_pk_fma_f32 v[36:37], v[94:95], v[44:45], v[36:37]
	v_lshlrev_b32_e32 v44, 16, v38
	v_mul_f32_e32 v40, 0xbfb8aa3b, v36
	v_mul_f32_e32 v41, 0xbfb8aa3b, v37
	v_exp_f32_e32 v40, v40
	v_exp_f32_e32 v41, v41
	v_and_b32_e32 v45, 0xffff0000, v38
	v_pk_mul_f32 v[44:45], v[52:53], v[44:45]
	v_add_f32_e32 v40, 1.0, v40
	v_add_f32_e32 v41, 1.0, v41
	v_rcp_f32_e32 v40, v40
	v_rcp_f32_e32 v41, v41
	v_and_b32_e32 v59, 0xffff0000, v46
	v_lshlrev_b32_e32 v46, 16, v4
	v_pk_mul_f32 v[36:37], v[36:37], v[40:41]
	v_lshlrev_b32_e32 v40, 16, v42
	v_and_b32_e32 v41, 0xffff0000, v42
	v_pk_fma_f32 v[40:41], v[48:49], v[40:41], v[44:45]
	v_lshlrev_b32_e32 v42, 16, v43
	s_waitcnt vmcnt(0)
	v_pk_fma_f32 v[40:41], v[60:61], v[58:59], v[40:41]
	v_and_b32_e32 v43, 0xffff0000, v43
	v_mul_f32_e32 v38, 0xbfb8aa3b, v40
	v_exp_f32_e32 v38, v38
	s_nop 0
	v_add_f32_e32 v38, 1.0, v38
	v_rcp_f32_e32 v44, v38
	v_mul_f32_e32 v38, 0xbfb8aa3b, v41
	v_exp_f32_e32 v38, v38
	s_nop 0
	v_add_f32_e32 v38, 1.0, v38
	v_rcp_f32_e32 v45, v38
	v_lshlrev_b32_e32 v38, 16, v39
	v_and_b32_e32 v39, 0xffff0000, v39
	v_pk_mul_f32 v[38:39], v[54:55], v[38:39]
	v_pk_mul_f32 v[40:41], v[40:41], v[44:45]
	v_lshlrev_b32_e32 v44, 16, v47
	v_and_b32_e32 v45, 0xffff0000, v47
	v_pk_fma_f32 v[38:39], v[50:51], v[42:43], v[38:39]
	v_and_b32_e32 v47, 0xffff0000, v4
	v_pk_fma_f32 v[38:39], v[62:63], v[44:45], v[38:39]
	v_lshlrev_b32_e32 v44, 16, v0
	v_mul_f32_e32 v42, 0xbfb8aa3b, v38
	v_mul_f32_e32 v43, 0xbfb8aa3b, v39
	v_exp_f32_e32 v42, v42
	v_exp_f32_e32 v43, v43
	v_and_b32_e32 v45, 0xffff0000, v0
	v_pk_mul_f32 v[28:29], v[28:29], v[44:45]
	v_add_f32_e32 v42, 1.0, v42
	v_add_f32_e32 v43, 1.0, v43
	v_rcp_f32_e32 v42, v42
	v_rcp_f32_e32 v43, v43
	v_lshlrev_b32_e32 v4, 16, v5
	v_and_b32_e32 v5, 0xffff0000, v5
	v_pk_mul_f32 v[38:39], v[38:39], v[42:43]
	v_lshlrev_b32_e32 v42, 16, v8
	v_and_b32_e32 v43, 0xffff0000, v8
	v_pk_fma_f32 v[20:21], v[20:21], v[42:43], v[28:29]
	v_lshlrev_b32_e32 v8, 16, v9
	v_pk_fma_f32 v[20:21], v[32:33], v[46:47], v[20:21]
	v_and_b32_e32 v9, 0xffff0000, v9
	v_mul_f32_e32 v0, 0xbfb8aa3b, v20
	v_exp_f32_e32 v0, v0
	s_nop 0
	v_add_f32_e32 v0, 1.0, v0
	v_rcp_f32_e32 v28, v0
	v_mul_f32_e32 v0, 0xbfb8aa3b, v21
	v_exp_f32_e32 v0, v0
	s_nop 0
	v_add_f32_e32 v0, 1.0, v0
	v_rcp_f32_e32 v29, v0
	v_lshlrev_b32_e32 v0, 16, v1
	v_and_b32_e32 v1, 0xffff0000, v1
	v_pk_mul_f32 v[0:1], v[30:31], v[0:1]
	v_pk_mul_f32 v[20:21], v[20:21], v[28:29]
	v_pk_fma_f32 v[0:1], v[22:23], v[8:9], v[0:1]
	v_lshlrev_b32_e32 v8, 16, v2
	v_pk_fma_f32 v[0:1], v[34:35], v[4:5], v[0:1]
	v_and_b32_e32 v9, 0xffff0000, v2
	v_mul_f32_e32 v4, 0xbfb8aa3b, v0
	v_mul_f32_e32 v5, 0xbfb8aa3b, v1
	v_exp_f32_e32 v4, v4
	v_exp_f32_e32 v5, v5
	v_pk_mul_f32 v[8:9], v[16:17], v[8:9]
	v_lshlrev_b32_e32 v22, 16, v6
	v_add_f32_e32 v4, 1.0, v4
	v_add_f32_e32 v5, 1.0, v5
	v_rcp_f32_e32 v4, v4
	v_rcp_f32_e32 v5, v5
	v_and_b32_e32 v23, 0xffff0000, v6
	v_lshlrev_b32_e32 v6, 16, v7
	v_and_b32_e32 v7, 0xffff0000, v7
	v_pk_mul_f32 v[0:1], v[0:1], v[4:5]
	v_lshlrev_b32_e32 v4, 16, v10
	v_and_b32_e32 v5, 0xffff0000, v10
	v_pk_fma_f32 v[4:5], v[12:13], v[4:5], v[8:9]
	v_cvt_pk_bf16_f32 v13, v0, v1
	v_pk_fma_f32 v[4:5], v[24:25], v[22:23], v[4:5]
	v_cvt_pk_bf16_f32 v10, v40, v41
	v_mul_f32_e32 v2, 0xbfb8aa3b, v4
	v_exp_f32_e32 v2, v2
	v_cvt_pk_bf16_f32 v12, v20, v21
	v_add_f32_e32 v2, 1.0, v2
	v_rcp_f32_e32 v8, v2
	v_mul_f32_e32 v2, 0xbfb8aa3b, v5
	v_exp_f32_e32 v2, v2
	s_nop 0
	v_add_f32_e32 v2, 1.0, v2
	v_rcp_f32_e32 v9, v2
	v_lshlrev_b32_e32 v2, 16, v3
	v_and_b32_e32 v3, 0xffff0000, v3
	v_pk_mul_f32 v[2:3], v[18:19], v[2:3]
	v_pk_mul_f32 v[4:5], v[4:5], v[8:9]
	v_lshlrev_b32_e32 v8, 16, v11
	v_and_b32_e32 v9, 0xffff0000, v11
	v_pk_fma_f32 v[2:3], v[14:15], v[8:9], v[2:3]
	v_cvt_pk_bf16_f32 v8, v56, v57
	v_pk_fma_f32 v[2:3], v[26:27], v[6:7], v[2:3]
	v_cvt_pk_bf16_f32 v9, v36, v37
	v_mul_f32_e32 v6, 0xbfb8aa3b, v2
	v_mul_f32_e32 v7, 0xbfb8aa3b, v3
	v_exp_f32_e32 v6, v6
	v_exp_f32_e32 v7, v7
	v_cvt_pk_bf16_f32 v11, v38, v39
	v_cvt_pk_bf16_f32 v4, v4, v5
	v_add_f32_e32 v6, 1.0, v6
	v_add_f32_e32 v7, 1.0, v7
	v_rcp_f32_e32 v6, v6
	v_rcp_f32_e32 v7, v7
	s_nop 0
	v_pk_mul_f32 v[0:1], v[2:3], v[6:7]
	s_nop 0
	v_cvt_pk_bf16_f32 v0, v0, v1
	ds_write_b16 v190, v8 offset:35840
	ds_write_b16_d16_hi v190, v8 offset:36992
	ds_write_b16 v190, v9 offset:38144
	ds_write_b16_d16_hi v190, v9 offset:39296
	ds_write_b16 v190, v10 offset:40448
	ds_write_b16_d16_hi v190, v10 offset:41600
	ds_write_b16 v190, v11 offset:42752
	ds_write_b16_d16_hi v190, v11 offset:43904
	ds_write_b16 v190, v12 offset:45056
	ds_write_b16_d16_hi v190, v12 offset:46208
	ds_write_b16 v190, v13 offset:47360
	ds_write_b16_d16_hi v190, v13 offset:48512
	ds_write_b16 v190, v4 offset:49664
	ds_write_b16_d16_hi v190, v4 offset:50816
	ds_write_b16 v190, v0 offset:51968
	ds_write_b16_d16_hi v190, v0 offset:53120
	s_and_saveexec_b64 s[0:1], s[56:57]
	s_xor_b64 s[0:1], exec, s[0:1]
	s_ashr_i32 s3, s2, 31
	s_or_saveexec_b64 s[0:1], s[0:1]
	v_mov_b64_e32 v[0:1], s[2:3]
	s_xor_b64 exec, exec, s[0:1]
	s_cbranch_execz .LBB0_1132
	v_or_b32_e32 v0, s55, v102
	v_ashrrev_i32_e32 v1, 31, v0
	v_lshlrev_b64 v[0:1], 6, v[0:1]
	v_lshl_add_u64 v[0:1], v[84:85], 0, v[0:1]
	s_lshl_b32 s30, s54, 2
	v_lshl_add_u64 v[0:1], v[0:1], 0, s[30:31]
	v_mov_b32_e32 v2, v193
	v_mov_b32_e32 v3, v204
	s_mov_b64 s[56:57], s[46:47]
	s_mov_b64 s[80:81], s[50:51]
	s_mov_b64 s[74:75], s[70:71]
	s_mov_b64 s[70:71], s[52:53]
	s_mov_b64 s[52:53], s[44:45]
	s_mov_b64 s[88:89], s[42:43]
	s_mov_b64 s[66:67], s[36:37]
	s_mov_b32 s30, s38
	s_mov_b32 s3, 0xbfb8aa3b
	s_waitcnt vmcnt(0) lgkmcnt(0)
	v_mul_f32_e32 v0, 0xbfb8aa3b, v2
	v_exp_f32_e32 v0, v0
	s_nop 0
	v_add_f32_e32 v2, 1.0, v0
	v_or_b32_e32 v0, s54, v104
	s_mov_b64 s[54:55], s[76:77]
	s_mov_b64 s[76:77], s[40:41]
	s_mov_b64 s[50:51], s[18:19]
	v_ashrrev_i32_e32 v1, 31, v0
	s_mov_b64 s[48:49], s[16:17]
	s_mov_b64 s[46:47], s[14:15]
	s_mov_b64 s[44:45], s[12:13]
	s_mov_b64 s[42:43], s[10:11]
	s_mov_b64 s[40:41], s[8:9]
	s_mov_b64 s[38:39], s[6:7]
	s_mov_b64 s[36:37], s[4:5]
	v_readlane_b32 s4, v250, 0
	v_lshlrev_b64 v[0:1], 2, v[0:1]
	v_readlane_b32 s16, v250, 12
	v_readlane_b32 s17, v250, 13
	v_readlane_b32 s14, v250, 10
	v_readlane_b32 s15, v250, 11
	v_lshl_add_u64 v[4:5], s[16:17], 0, v[0:1]
	v_mov_b32_e32 v4, v205
	v_lshl_add_u64 v[0:1], s[14:15], 0, v[0:1]
	v_mov_b32_e32 v0, v221
	v_readlane_b32 s5, v250, 1
	v_readlane_b32 s6, v250, 2
	v_readlane_b32 s7, v250, 3
	v_readlane_b32 s8, v250, 4
	v_readlane_b32 s9, v250, 5
	v_readlane_b32 s10, v250, 6
	v_readlane_b32 s11, v250, 7
	v_readlane_b32 s12, v250, 8
	v_readlane_b32 s13, v250, 9
	v_readlane_b32 s18, v250, 14
	v_readlane_b32 s19, v250, 15
	s_mov_b64 s[4:5], s[36:37]
	s_mov_b64 s[6:7], s[38:39]
	s_mov_b64 s[8:9], s[40:41]
	s_mov_b64 s[10:11], s[42:43]
	s_mov_b64 s[12:13], s[44:45]
	s_mov_b64 s[14:15], s[46:47]
	s_mov_b64 s[16:17], s[48:49]
	s_mov_b64 s[18:19], s[50:51]
	s_mov_b64 s[40:41], s[76:77]
	s_mov_b64 s[76:77], s[54:55]
	v_readlane_b32 s54, v254, 59
	v_readlane_b32 s55, v254, 60
	v_rcp_f32_e32 v2, v2
	s_movk_i32 s39, 0x1600
	s_mov_b32 s38, s30
	s_mov_b64 s[36:37], s[66:67]
	s_mov_b64 s[42:43], s[88:89]
	s_mov_b64 s[44:45], s[52:53]
	s_mov_b64 s[52:53], s[70:71]
	s_mov_b64 s[70:71], s[74:75]
	s_mov_b64 s[50:51], s[80:81]
	s_mov_b64 s[46:47], s[56:57]
	s_waitcnt vmcnt(1)
	v_add_f32_e32 v3, v3, v4
	v_max_f32_e32 v6, 0, v3
	v_mul_f32_e64 v3, |v3|, s3
	v_exp_f32_e32 v3, v3
	s_mov_b32 s3, 0x3f2aaaab
	s_waitcnt vmcnt(0)
	v_mul_f32_e32 v0, 0x3fb8aa3b, v0
	v_exp_f32_e32 v0, v0
	v_add_f32_e32 v7, 1.0, v3
	v_add_f32_e32 v4, -1.0, v7
	v_sub_f32_e32 v5, v4, v7
	v_add_f32_e32 v5, 1.0, v5
	v_sub_f32_e32 v4, v3, v4
	v_add_f32_e32 v8, v4, v5
	v_frexp_mant_f32_e32 v4, v7
	v_cmp_gt_f32_e32 vcc, s3, v4
	v_cvt_f64_f32_e32 v[4:5], v7
	v_frexp_exp_i32_f64_e32 v4, v[4:5]
	v_subbrev_co_u32_e32 v4, vcc, 0, v4, vcc
	v_sub_u32_e32 v5, 0, v4
	v_ldexp_f32 v7, v7, v5
	v_ldexp_f32 v5, v8, v5
	v_add_f32_e32 v8, -1.0, v7
	v_add_f32_e32 v9, 1.0, v8
	v_sub_f32_e32 v9, v7, v9
	v_add_f32_e32 v9, v5, v9
	v_add_f32_e32 v10, v8, v9
	v_sub_f32_e32 v8, v10, v8
	v_sub_f32_e32 v8, v9, v8
	v_add_f32_e32 v9, 1.0, v7
	v_add_f32_e32 v11, -1.0, v9
	v_sub_f32_e32 v7, v7, v11
	v_add_f32_e32 v5, v5, v7
	v_add_f32_e32 v7, v9, v5
	v_sub_f32_e32 v9, v7, v9
	v_sub_f32_e32 v5, v5, v9
	v_rcp_f32_e32 v9, v7
	v_cvt_f32_i32_e32 v4, v4
	s_mov_b32 s3, 0x3f317218
	v_mul_f32_e32 v11, v10, v9
	v_mul_f32_e32 v12, v7, v11
	v_fma_f32 v13, v11, v7, -v12
	v_fmac_f32_e32 v13, v11, v5
	v_add_f32_e32 v14, v12, v13
	v_sub_f32_e32 v15, v10, v14
	v_sub_f32_e32 v10, v10, v15
	v_sub_f32_e32 v12, v14, v12
	v_sub_f32_e32 v10, v10, v14
	v_add_f32_e32 v8, v8, v10
	v_sub_f32_e32 v10, v12, v13
	v_add_f32_e32 v8, v10, v8
	v_add_f32_e32 v10, v15, v8
	v_mul_f32_e32 v12, v9, v10
	v_mul_f32_e32 v13, v7, v12
	v_fma_f32 v7, v12, v7, -v13
	v_fmac_f32_e32 v7, v12, v5
	v_sub_f32_e32 v5, v15, v10
	v_add_f32_e32 v5, v8, v5
	v_add_f32_e32 v8, v13, v7
	v_sub_f32_e32 v14, v10, v8
	v_sub_f32_e32 v10, v10, v14
	v_sub_f32_e32 v13, v8, v13
	v_sub_f32_e32 v8, v10, v8
	v_add_f32_e32 v5, v5, v8
	v_sub_f32_e32 v7, v13, v7
	v_add_f32_e32 v5, v7, v5
	v_add_f32_e32 v7, v11, v12
	v_add_f32_e32 v5, v14, v5
	v_sub_f32_e32 v8, v7, v11
	v_mul_f32_e32 v5, v9, v5
	v_sub_f32_e32 v8, v12, v8
	v_add_f32_e32 v5, v8, v5
	v_mul_f32_e32 v11, 0x3f317218, v4
	v_add_f32_e32 v8, v7, v5
	v_fma_f32 v12, v4, s3, -v11
	v_mul_f32_e32 v9, v8, v8
	v_fmac_f32_e32 v12, 0xb102e308, v4
	v_sub_f32_e32 v4, v8, v7
	v_fmamk_f32 v10, v9, 0x3e9b6dac, v207
	v_sub_f32_e32 v4, v5, v4
	v_add_f32_e32 v5, v11, v12
	v_fmaak_f32 v10, v9, v10, 0x3f2aaada
	v_sub_f32_e32 v7, v5, v11
	v_ldexp_f32 v11, v8, 1
	v_mul_f32_e32 v8, v8, v9
	v_mul_f32_e32 v8, v8, v10
	v_add_f32_e32 v9, v11, v8
	v_sub_f32_e32 v10, v9, v11
	v_ldexp_f32 v4, v4, 1
	v_sub_f32_e32 v8, v8, v10
	v_add_f32_e32 v4, v4, v8
	v_add_f32_e32 v8, v9, v4
	v_sub_f32_e32 v9, v8, v9
	v_sub_f32_e32 v4, v4, v9
	v_add_f32_e32 v9, v5, v8
	v_sub_f32_e32 v10, v9, v5
	v_sub_f32_e32 v11, v9, v10
	v_sub_f32_e32 v7, v12, v7
	v_sub_f32_e32 v5, v5, v11
	v_sub_f32_e32 v8, v8, v10
	v_add_f32_e32 v5, v8, v5
	v_add_f32_e32 v8, v7, v4
	v_sub_f32_e32 v10, v8, v7
	v_sub_f32_e32 v11, v8, v10
	v_sub_f32_e32 v7, v7, v11
	v_sub_f32_e32 v4, v4, v10
	v_add_f32_e32 v5, v8, v5
	v_add_f32_e32 v4, v4, v7
	v_add_f32_e32 v7, v9, v5
	v_sub_f32_e32 v8, v7, v9
	v_sub_f32_e32 v5, v5, v8
	v_add_f32_e32 v4, v4, v5
	s_mov_b32 s3, 0x7f800000
	v_add_f32_e32 v4, v7, v4
	v_cmp_neq_f32_e32 vcc, s3, v3
	s_mov_b32 s3, 0x33800000
	s_nop 0
	v_cndmask_b32_e32 v4, v214, v4, vcc
	v_cmp_ngt_f32_e32 vcc, -1.0, v3
	s_nop 1
	v_cndmask_b32_e32 v4, v215, v4, vcc
	v_cmp_neq_f32_e32 vcc, -1.0, v3
	s_nop 1
	v_cndmask_b32_e32 v4, v216, v4, vcc
	v_cmp_lt_f32_e64 vcc, |v3|, s3
	s_ashr_i32 s3, s2, 31
	s_nop 0
	v_cndmask_b32_e32 v3, v4, v3, vcc
	v_add_f32_e32 v3, v6, v3
	v_mul_f32_e64 v1, v3, -v0
	ds_bpermute_b32 v4, v143, v1
	s_waitcnt lgkmcnt(0)
	v_fma_f32 v4, v3, -v0, v4
	v_cndmask_b32_e64 v1, v4, v1, s[54:55]
	ds_bpermute_b32 v4, v144, v1
	v_readlane_b32 s54, v254, 61
	v_readlane_b32 s55, v254, 62
	s_waitcnt lgkmcnt(0)
	v_add_f32_e32 v4, v1, v4
	v_cndmask_b32_e64 v1, v4, v1, s[54:55]
	ds_bpermute_b32 v4, v145, v1
	v_readlane_b32 s54, v254, 63
	v_readlane_b32 s55, v255, 0
	s_waitcnt lgkmcnt(0)
	v_add_f32_e32 v4, v1, v4
	v_cndmask_b32_e64 v1, v4, v1, s[54:55]
	ds_bpermute_b32 v4, v146, v1
	v_readlane_b32 s54, v255, 1
	v_readlane_b32 s55, v255, 2
	s_waitcnt lgkmcnt(0)
	v_add_f32_e32 v4, v1, v4
	v_cndmask_b32_e64 v1, v4, v1, s[54:55]
	ds_bpermute_b32 v4, v147, v1
	v_readlane_b32 s54, v255, 3
	v_readlane_b32 s55, v255, 4
	s_waitcnt lgkmcnt(0)
	v_add_f32_e32 v4, v1, v4
	v_cndmask_b32_e64 v1, v4, v1, s[54:55]
	ds_bpermute_b32 v4, v148, v1
	v_readlane_b32 s54, v255, 5
	v_readlane_b32 s55, v255, 6
	s_waitcnt lgkmcnt(0)
	v_add_f32_e32 v4, v1, v4
	v_cndmask_b32_e64 v1, v4, v1, s[54:55]
	ds_bpermute_b32 v4, v149, v1
	v_readlane_b32 s54, v254, 57
	v_readlane_b32 s55, v254, 58
	s_waitcnt lgkmcnt(0)
	v_sub_f32_e32 v4, v4, v1
	v_fma_f32 v0, v3, -v0, v4
	v_cndmask_b32_e64 v3, v0, v1, s[54:55]
	s_lshl_b64 s[54:55], s[2:3], 9
	v_lshl_add_u64 v[0:1], v[66:67], 0, s[54:55]
	ds_write_b32 v105, v3
	ds_write_b32 v106, v2
	flat_store_dword v[0:1], v3
	v_mov_b64_e32 v[0:1], s[2:3]
